# state-output copy loops (pool/win prompt, pool sample) moved to the workgroups at the end of the grid
# speedup vs baseline: 1.0033x; 1.0033x over previous
; __device__ __forceinline__ void store8f(float* dst, const u32x4& x) { float f[8]; unpack8(x, f); *(f32x4*)dst = (f32x4){f[0], f[1], f[2], f[3]}; *(f32x4*)(dst + 4) = (f32x4){f[4], f[5], f[6], f[7]}; }
; __device__ __forceinline__ void s2_state_outputs(Frame& F, int l) {
;     const bf16_t* P = (const bf16_t*)(F.ws + WS_P);
;     const int gt = F.gw * 64 + F.lane, ngt = F.ngw * 64;
;     for (int it = gt; it < PB * 15 * 128; it += ngt) { const int c0 = (it & 127) * 8, r = (it >> 7) % 15, b = (it >> 7) / 15;
;         store8f(F.out + O_POOLP + (((size_t)l * PB + b) * 15 + r) * 1024 + c0, *(const u32x4*)(P + (size_t)(b * SEQ + SEQ - 15 + r) * NPROJ + C_PU + c0)); }
.LBB0_543:
	v_readlane_b32 s24, v252, 0
	v_readlane_b32 s26, v252, 2
	v_readlane_b32 s27, v252, 3
	v_mov_b32_e32 v2, v0
	s_mov_b64 s[16:17], s[26:27]
	s_add_u32 s40, s16, 0xc800000
	v_readfirstlane_b32 s4, v2
	v_readlane_b32 s8, v253, 27
	s_addc_u32 s41, s17, 0
	s_sub_i32 s8, s91, s8
	s_addk_i32 s8, 0xfe00
	s_add_i32 s4, s4, s8
	v_mov_b32_e32 v3, s4
	s_movk_i32 s8, 0xffc0
	v_readlane_b32 s25, v252, 1
	v_bfi_b32 v14, s8, v3, v2
	s_movk_i32 s8, 0xf00
	v_and_b32_e32 v15, 63, v2
	s_mov_b64 s[22:23], s[24:25]
	v_cmp_gt_i32_e32 vcc, s8, v14
	s_and_saveexec_b64 s[24:25], vcc
	s_movk_i32 s14, 0xe00
	s_cbranch_execz .LBB0_546
	s_add_u32 s26, s22, 0x9480000
	s_addc_u32 s27, s23, 0
	s_lshl_b32 s8, s4, 3
	s_and_b32 s8, s8, 0xfffffe00
	v_lshl_or_b32 v2, v15, 3, s8
	s_mov_b64 s[28:29], 0
	v_mov_b32_e32 v3, v14

; #define FIN(i) ((const float*)(const GAS float*)(((const float* const __attribute__((address_space(4)))*)__builtin_amdgcn_kernarg_segment_ptr())[i]))
; __device__ __forceinline__ void store8f(float* dst, const u32x4& x) { float f[8]; unpack8(x, f); *(f32x4*)dst = (f32x4){f[0], f[1], f[2], f[3]}; *(f32x4*)(dst + 4) = (f32x4){f[4], f[5], f[6], f[7]}; }
; __device__ __forceinline__ void s2_state_outputs(Frame& F, int l) {
;     const bf16_t* P = (const bf16_t*)(F.ws + WS_P);
;     const int gt = F.gw * 64 + F.lane, ngt = F.ngw * 64;
;     ...
;     for (int it = gt; it < SB * 512 * 64; it += ngt) { const int c0 = (it & 63) * 8, r = (it >> 6) & 511, b = it >> 15;
;         float* dst = F.out + O_WINS + (((size_t)l * SB + b) * 512 + r) * 512 + c0;
;         if (r < 508) { const float* sp = FIN(IN_SWIN) + (((size_t)l * SB + b) * 512 + r + 4) * 512 + c0; *(f32x4*)dst = *(const f32x4*)sp; *(f32x4*)(dst + 4) = *(const f32x4*)(sp + 4); }
;         else store8f(dst, *(const u32x4*)(P + (size_t)(MPT + b * 4 + r - 508) * NPROJ + C_WK + c0)); }
.LBB0_556:
	s_or_b64 exec, exec, s[24:25]
	v_readlane_b32 s8, v253, 27
	s_nop 3
	s_sub_i32 s4, s4, s91
	s_addk_i32 s4, 0x200
	s_add_i32 s4, s4, s8
	s_add_i32 s4, s4, s8
	s_movk_i32 s8, 0xffc0
	v_mov_b32_e32 v3, s4
	v_bfi_b32 v14, s8, v3, v0
	v_cmp_gt_i32_e32 vcc, s38, v14
	s_and_saveexec_b64 s[24:25], vcc
	s_cbranch_execz .LBB0_563
	s_add_u32 s22, s22, 0x8480000
	s_addc_u32 s23, s23, 0
	s_lshl_b32 s4, s4, 3
	s_and_b32 s4, s4, 0xfffffe00
	v_lshl_or_b32 v12, v15, 3, s4
	s_mov_b64 s[26:27], 0
	s_branch .LBB0_559
